# touch-wait removal in 4 tile loops + L2 prefetch of retention initial states
# baseline (speedup 1.0000x reference)
.LBB0_413:
	s_cmp_gt_i32 s73, 5
	s_cselect_b64 s[6:7], -1, 0
	s_add_u32 s42, s70, 0x4b000000
	s_addc_u32 s43, s71, 0
	s_and_b64 s[4:5], s[4:5], s[6:7]
	s_andn2_b64 vcc, exec, s[4:5]
	s_cbranch_vccnz .LBB0_455
	s_lshl_b32 s3, s2, 5
	s_and_b32 s3, s3, 0xe0
	s_ashr_i32 s4, s2, 3
	s_add_i32 s3, s3, s4
	s_cmpk_eq_i32 s33, 0x100
	s_cselect_b32 s38, s3, s2
	s_cmpk_gt_i32 s38, 0xff
	s_cbranch_scc1 .LBB0_455
	s_bfe_u32 s25, s38, 0x30003
	s_lshl_b32 s3, s25, 2
	v_readlane_b32 s4, v255, 2
	v_mov_b32_e32 v1, s3
	v_readlane_b32 s5, v255, 3
	v_readlane_b32 s6, v255, 4
	v_readlane_b32 s7, v255, 5
	v_readlane_b32 s8, v255, 6
	v_readlane_b32 s9, v255, 7
	v_readlane_b32 s10, v255, 8
	v_readlane_b32 s11, v255, 9
	v_readlane_b32 s12, v255, 10
	v_readlane_b32 s13, v255, 11
	v_readlane_b32 s14, v255, 12
	v_readlane_b32 s15, v255, 13
	v_readlane_b32 s16, v255, 14
	v_readlane_b32 s17, v255, 15
	v_readlane_b32 s18, v255, 16
	v_readlane_b32 s19, v255, 17
	s_movk_i32 s3, 0x80
	v_cmp_gt_u32_e64 s[20:21], s3, v0
	s_movk_i32 s3, 0x7f
	v_cmp_lt_u32_e32 vcc, s3, v0
	s_nop 0
	global_load_dword v2, v1, s[18:19]
	v_readlane_b32 s4, v255, 22
	v_readlane_b32 s5, v255, 23
	v_readlane_b32 s6, v255, 24
	v_readlane_b32 s7, v255, 25
	v_readlane_b32 s8, v255, 26
	v_readlane_b32 s9, v255, 27
	v_readlane_b32 s10, v255, 28
	global_load_dword v1, v1, s[4:5]
	v_readlane_b32 s11, v255, 29
	v_readlane_b32 s12, v255, 30
	v_readlane_b32 s13, v255, 31
	v_readlane_b32 s14, v255, 32
	v_readlane_b32 s15, v255, 33
	v_readlane_b32 s16, v255, 34
	v_readlane_b32 s17, v255, 35
	v_readlane_b32 s18, v255, 36
	v_readlane_b32 s19, v255, 37
	s_waitcnt vmcnt(0)
	v_readlane_b32 s78, v255, 41
	v_readlane_b32 s79, v255, 42
	v_readlane_b32 s80, v255, 43
	v_readlane_b32 s81, v255, 44
	s_lshr_b32 s82, s38, 3
	s_lshl_b32 s82, s82, 17
	v_lshl_add_u32 v82, v0, 7, s82
	v_add_u32_e32 v83, 0x10000, v82
	s_nop 1
	global_load_dword v84, v82, s[78:79]
	global_load_dword v84, v83, s[78:79]
	global_load_dword v84, v82, s[80:81]
	global_load_dword v84, v83, s[80:81]
	v_mul_f32_e32 v2, 0x3fb8aa3b, v2
	v_mul_f32_e32 v3, 0x3fb8aa3b, v1
	v_exp_f32_e32 v1, v2
	v_exp_f32_e32 v2, v3
	s_and_saveexec_b64 s[6:7], vcc
	s_xor_b64 s[6:7], exec, s[6:7]
	v_lshrrev_b32_e32 v254, 3, v0
	s_or_saveexec_b64 s[6:7], s[6:7]
	v_mul_f32_e32 v197, 0xbfb8aa3b, v1
	v_mul_f32_e32 v81, 0xbfb8aa3b, v2
	v_lshlrev_b32_e32 v1, 1, v0
	v_and_b32_e32 v194, 3, v0
	s_xor_b64 exec, exec, s[6:7]
	s_cbranch_execz .LBB0_419
	v_lshrrev_b32_e32 v254, 3, v0
	v_and_or_b32 v1, v1, 56, v194
	v_and_b32_e32 v2, 4, v254
	v_or_b32_e32 v3, v1, v2
	v_bitop3_b32 v1, v1, 63, v2 bitop3:0x36
	v_cmp_gt_u32_e32 vcc, 64, v0
	s_nop 1
	v_cndmask_b32_e32 v1, v3, v1, vcc
	v_cndmask_b32_e32 v2, v81, v197, vcc
	v_cvt_f32_ubyte0_e32 v1, v1
	v_mul_f32_e32 v1, v2, v1
	v_exp_f32_e32 v1, v1
	v_lshl_add_u32 v2, v0, 2, 0
	v_add_u32_e32 v2, 0x21400, v2
	v_mul_f32_e32 v1, 0x3d800000, v1
	ds_write_b32 v2, v1

.LBB0_421:
	s_cmp_lt_u32 s9, 15
	s_cselect_b64 s[62:63], -1, 0
	s_cmp_gt_u32 s9, 14
	s_cbranch_scc1 .LBB0_423
	v_lshl_add_u64 v[82:83], s[70:71], 0, v[182:183]
	v_add_co_u32_e32 v84, vcc, 0x1ee61000, v82
	v_lshl_add_u64 v[86:87], s[70:71], 0, v[172:173]
	s_nop 0
	v_addc_co_u32_e32 v85, vcc, 0, v83, vcc
	global_load_dwordx4 v[130:133], v[84:85], off
	global_load_dwordx4 v[134:137], v[86:87], off
	v_add_co_u32_e32 v84, vcc, 0x1eef9000, v82
	v_lshl_add_u64 v[86:87], s[70:71], 0, v[176:177]
	s_nop 0
	v_addc_co_u32_e32 v85, vcc, 0, v83, vcc
	global_load_dwordx4 v[138:141], v[84:85], off
	global_load_dwordx4 v[142:145], v[86:87], off
	v_add_co_u32_e32 v84, vcc, 0x1ef91000, v82
	v_lshl_add_u64 v[86:87], s[70:71], 0, v[178:179]
	s_nop 0
	v_addc_co_u32_e32 v85, vcc, 0, v83, vcc
	v_add_co_u32_e32 v82, vcc, 0x1f029000, v82
	global_load_dwordx4 v[146:149], v[84:85], off
	global_load_dwordx4 v[150:153], v[86:87], off
	v_addc_co_u32_e32 v83, vcc, 0, v83, vcc
	v_lshl_add_u64 v[84:85], s[70:71], 0, v[180:181]
	global_load_dwordx4 v[154:157], v[82:83], off
	global_load_dwordx4 v[158:161], v[84:85], off
.LBB0_423:
	ds_read_b128 v[82:85], v219
	ds_read_b128 v[86:89], v213
	s_min_u32 s10, s9, 13
	v_lshl_add_u32 v94, s10, 6, v167
	v_mul_u32_u24_e32 v168, 0x9800, v94
	s_add_i32 s24, s44, s37
	s_waitcnt lgkmcnt(0)
	v_mfma_f32_32x32x16_bf16 v[98:113], v[82:85], v[86:89], 0
	ds_read_b128 v[82:85], v219 offset:32
	ds_read_b128 v[86:89], v213 offset:32
	v_add_u32_e32 v94, s37, v2
	s_cmp_lt_u32 s9, s36
	v_subrev_u32_e32 v94, 63, v94
	s_cselect_b64 vcc, -1, 0
	v_cndmask_b32_e32 v114, v81, v197, vcc
	s_and_b64 s[10:11], vcc, exec
	s_waitcnt lgkmcnt(0)
	v_mfma_f32_32x32x16_bf16 v[98:113], v[82:85], v[86:89], v[98:113]
	ds_read_b128 v[82:85], v219 offset:64
	ds_read_b128 v[86:89], v213 offset:64
	s_cselect_b32 s10, 0, 0x100
	s_cmp_lg_u32 s24, 0
	s_cselect_b64 s[86:87], -1, 0
	s_cmp_eq_u32 s24, 0
	s_waitcnt lgkmcnt(0)
	v_mfma_f32_32x32x16_bf16 v[98:113], v[82:85], v[86:89], v[98:113]
	ds_read_b128 v[82:85], v219 offset:96
	ds_read_b128 v[86:89], v213 offset:96
	s_waitcnt lgkmcnt(0)
	v_mfma_f32_32x32x16_bf16 v[98:113], v[82:85], v[86:89], v[98:113]
	ds_read_b128 v[82:85], v219 offset:128
	ds_read_b128 v[86:89], v213 offset:128
	s_waitcnt lgkmcnt(0)
	v_mfma_f32_32x32x16_bf16 v[98:113], v[82:85], v[86:89], v[98:113]
	ds_read_b128 v[82:85], v219 offset:160
	ds_read_b128 v[86:89], v213 offset:160
	s_waitcnt lgkmcnt(0)
	v_mfma_f32_32x32x16_bf16 v[98:113], v[82:85], v[86:89], v[98:113]
	ds_read_b128 v[82:85], v219 offset:192
	ds_read_b128 v[86:89], v213 offset:192
	s_waitcnt lgkmcnt(0)
	v_mfma_f32_32x32x16_bf16 v[98:113], v[82:85], v[86:89], v[98:113]
	ds_read_b128 v[82:85], v219 offset:224
	ds_read_b128 v[86:89], v213 offset:224
	ds_read_b128 v[90:93], v219 offset:256
	s_waitcnt lgkmcnt(1)
	v_mfma_f32_32x32x16_bf16 v[98:113], v[82:85], v[86:89], v[98:113]
	v_lshl_add_u64 v[82:83], v[170:171], 0, v[168:169]
	global_load_dword v251, v[82:83], off
	ds_read_b128 v[82:85], v213 offset:256
	s_waitcnt lgkmcnt(0)
	v_mfma_f32_32x32x16_bf16 v[98:113], v[90:93], v[82:85], v[98:113]
	ds_read_b128 v[82:85], v219 offset:288
	ds_read_b128 v[86:89], v213 offset:288
	s_waitcnt lgkmcnt(0)
	v_mfma_f32_32x32x16_bf16 v[98:113], v[82:85], v[86:89], v[98:113]
	ds_read_b128 v[82:85], v219 offset:320
	ds_read_b128 v[86:89], v213 offset:320
	s_waitcnt lgkmcnt(0)
	v_mfma_f32_32x32x16_bf16 v[98:113], v[82:85], v[86:89], v[98:113]
	ds_read_b128 v[82:85], v219 offset:352
	ds_read_b128 v[86:89], v213 offset:352
	s_waitcnt lgkmcnt(0)
	v_mfma_f32_32x32x16_bf16 v[98:113], v[82:85], v[86:89], v[98:113]
	ds_read_b128 v[82:85], v219 offset:384
	ds_read_b128 v[86:89], v213 offset:384
	s_waitcnt lgkmcnt(0)
	v_mfma_f32_32x32x16_bf16 v[98:113], v[82:85], v[86:89], v[98:113]
	ds_read_b128 v[82:85], v219 offset:416
	ds_read_b128 v[86:89], v213 offset:416
	ds_read_b128 v[90:93], v219 offset:448
	s_waitcnt lgkmcnt(1)
	v_mfma_f32_32x32x16_bf16 v[98:113], v[82:85], v[86:89], v[98:113]
	ds_read_b128 v[82:85], v213 offset:448
	v_cndmask_b32_e32 v86, v203, v94, vcc
	v_cvt_f32_i32_e32 v115, v86
	ds_read_b128 v[86:89], v213 offset:480
	ds_read_b128 v[94:97], v219 offset:480
	s_waitcnt lgkmcnt(2)
	v_mfma_f32_32x32x16_bf16 v[98:113], v[90:93], v[82:85], v[98:113]
	v_mul_f32_e32 v82, v114, v115
	v_exp_f32_e32 v114, v82
	v_add_u32_e32 v115, s10, v216
	s_waitcnt lgkmcnt(0)
	v_mfma_f32_32x32x16_bf16 v[98:113], v[94:97], v[86:89], v[98:113]
	s_cbranch_scc1 .LBB0_431
	ds_read_b128 v[82:85], v115
	ds_read_b128 v[86:89], v115 offset:16
	ds_read_b128 v[90:93], v115 offset:32
	ds_read_b128 v[94:97], v115 offset:48
	s_waitcnt lgkmcnt(3)
	v_pk_mul_f32 v[84:85], v[114:115], v[84:85] op_sel_hi:[0,1]
	s_waitcnt lgkmcnt(2)
	v_pk_mul_f32 v[88:89], v[114:115], v[88:89] op_sel_hi:[0,1]
	s_waitcnt lgkmcnt(1)
	v_pk_mul_f32 v[92:93], v[114:115], v[92:93] op_sel_hi:[0,1]
	s_waitcnt lgkmcnt(0)
	v_pk_mul_f32 v[96:97], v[114:115], v[96:97] op_sel_hi:[0,1]
	v_pk_mul_f32 v[82:83], v[114:115], v[82:83] op_sel_hi:[0,1]
	v_pk_mul_f32 v[86:87], v[114:115], v[86:87] op_sel_hi:[0,1]
	v_pk_mul_f32 v[90:91], v[114:115], v[90:91] op_sel_hi:[0,1]
	v_pk_mul_f32 v[94:95], v[114:115], v[94:95] op_sel_hi:[0,1]
	v_pk_mul_f32 v[94:95], v[110:111], v[94:95]
	v_pk_mul_f32 v[90:91], v[106:107], v[90:91]
	v_pk_mul_f32 v[86:87], v[102:103], v[86:87]
	v_pk_mul_f32 v[96:97], v[112:113], v[96:97]
	v_pk_mul_f32 v[92:93], v[108:109], v[92:93]
	v_pk_mul_f32 v[88:89], v[104:105], v[88:89]
	v_pk_mul_f32 v[84:85], v[100:101], v[84:85]
	v_pk_mul_f32 v[82:83], v[98:99], v[82:83]
	s_cbranch_execnz .LBB0_426

.LBB0_441:
	s_cmp_lt_u32 s30, 3
	s_cselect_b64 s[86:87], -1, 0
	s_cmp_gt_u32 s30, 2
	s_cbranch_scc1 .LBB0_443
	v_lshl_add_u64 v[82:83], s[70:71], 0, v[194:195]
	v_add_co_u32_e32 v84, vcc, 0x1ee61000, v82
	v_lshl_add_u64 v[86:87], s[70:71], 0, v[196:197]
	s_nop 0
	v_addc_co_u32_e32 v85, vcc, 0, v83, vcc
	global_load_dwordx4 v[130:133], v[84:85], off
	global_load_dwordx4 v[134:137], v[86:87], off
	v_add_co_u32_e32 v84, vcc, 0x1eef9000, v82
	v_lshl_add_u64 v[86:87], s[70:71], 0, v[198:199]
	s_nop 0
	v_addc_co_u32_e32 v85, vcc, 0, v83, vcc
	global_load_dwordx4 v[138:141], v[84:85], off
	global_load_dwordx4 v[142:145], v[86:87], off
	v_add_co_u32_e32 v84, vcc, 0x1ef91000, v82
	v_lshl_add_u64 v[86:87], s[70:71], 0, v[200:201]
	s_nop 0
	v_addc_co_u32_e32 v85, vcc, 0, v83, vcc
	v_add_co_u32_e32 v82, vcc, 0x1f029000, v82
	global_load_dwordx4 v[146:149], v[84:85], off
	global_load_dwordx4 v[150:153], v[86:87], off
	v_addc_co_u32_e32 v83, vcc, 0, v83, vcc
	v_lshl_add_u64 v[84:85], s[70:71], 0, v[202:203]
	global_load_dwordx4 v[154:157], v[82:83], off
	global_load_dwordx4 v[158:161], v[84:85], off
.LBB0_443:
	ds_read_b128 v[82:85], v219
	ds_read_b128 v[86:89], v213
	s_add_i32 s24, s46, s63
	s_cmp_eq_u32 s63, 0
	s_movk_i32 s10, 0x80
	s_cselect_b32 s10, s10, 0xc0
	s_waitcnt lgkmcnt(0)
	v_mfma_f32_32x32x16_bf16 v[98:113], v[82:85], v[86:89], 0
	ds_read_b128 v[82:85], v219 offset:32
	ds_read_b128 v[86:89], v213 offset:32
	v_or_b32_e32 v94, s10, v214
	v_mul_u32_u24_e32 v166, 0x9800, v94
	v_add_u32_e32 v94, s63, v171
	s_cmp_lt_u32 s30, s81
	v_subrev_u32_e32 v94, 63, v94
	s_cselect_b64 vcc, -1, 0
	s_waitcnt lgkmcnt(0)
	v_mfma_f32_32x32x16_bf16 v[98:113], v[82:85], v[86:89], v[98:113]
	ds_read_b128 v[82:85], v219 offset:64
	ds_read_b128 v[86:89], v213 offset:64
	v_cndmask_b32_e32 v114, v169, v81, vcc
	s_and_b64 s[10:11], vcc, exec
	s_cselect_b32 s10, 0, 0x100
	s_cmp_lg_u32 s24, 0
	s_cselect_b64 s[88:89], -1, 0
	s_cmp_eq_u32 s24, 0
	s_waitcnt lgkmcnt(0)
	v_mfma_f32_32x32x16_bf16 v[98:113], v[82:85], v[86:89], v[98:113]
	ds_read_b128 v[82:85], v219 offset:96
	ds_read_b128 v[86:89], v213 offset:96
	s_waitcnt lgkmcnt(0)
	v_mfma_f32_32x32x16_bf16 v[98:113], v[82:85], v[86:89], v[98:113]
	ds_read_b128 v[82:85], v219 offset:128
	ds_read_b128 v[86:89], v213 offset:128
	s_waitcnt lgkmcnt(0)
	v_mfma_f32_32x32x16_bf16 v[98:113], v[82:85], v[86:89], v[98:113]
	ds_read_b128 v[82:85], v219 offset:160
	ds_read_b128 v[86:89], v213 offset:160
	s_waitcnt lgkmcnt(0)
	v_mfma_f32_32x32x16_bf16 v[98:113], v[82:85], v[86:89], v[98:113]
	ds_read_b128 v[82:85], v219 offset:192
	ds_read_b128 v[86:89], v213 offset:192
	ds_read_b128 v[90:93], v219 offset:224
	s_waitcnt lgkmcnt(1)
	v_mfma_f32_32x32x16_bf16 v[98:113], v[82:85], v[86:89], v[98:113]
	ds_read_b128 v[82:85], v213 offset:224
	ds_read_b128 v[86:89], v219 offset:256
	s_waitcnt lgkmcnt(1)
	v_mfma_f32_32x32x16_bf16 v[98:113], v[90:93], v[82:85], v[98:113]
	v_lshl_add_u64 v[82:83], v[192:193], 0, v[166:167]
	global_load_dword v251, v[82:83], off
	ds_read_b128 v[82:85], v213 offset:256
	s_waitcnt lgkmcnt(0)
	v_mfma_f32_32x32x16_bf16 v[98:113], v[86:89], v[82:85], v[98:113]
	ds_read_b128 v[82:85], v219 offset:288
	ds_read_b128 v[86:89], v213 offset:288
	s_waitcnt lgkmcnt(0)
	v_mfma_f32_32x32x16_bf16 v[98:113], v[82:85], v[86:89], v[98:113]
	ds_read_b128 v[82:85], v219 offset:320
	ds_read_b128 v[86:89], v213 offset:320
	s_waitcnt lgkmcnt(0)
	v_mfma_f32_32x32x16_bf16 v[98:113], v[82:85], v[86:89], v[98:113]
	ds_read_b128 v[82:85], v219 offset:352
	ds_read_b128 v[86:89], v213 offset:352
	s_waitcnt lgkmcnt(0)
	v_mfma_f32_32x32x16_bf16 v[98:113], v[82:85], v[86:89], v[98:113]
	ds_read_b128 v[82:85], v219 offset:384
	ds_read_b128 v[86:89], v213 offset:384
	s_waitcnt lgkmcnt(0)
	v_mfma_f32_32x32x16_bf16 v[98:113], v[82:85], v[86:89], v[98:113]
	ds_read_b128 v[82:85], v219 offset:416
	ds_read_b128 v[86:89], v213 offset:416
	ds_read_b128 v[90:93], v219 offset:448
	s_waitcnt lgkmcnt(1)
	v_mfma_f32_32x32x16_bf16 v[98:113], v[82:85], v[86:89], v[98:113]
	ds_read_b128 v[82:85], v213 offset:448
	v_cndmask_b32_e32 v86, v232, v94, vcc
	v_cvt_f32_i32_e32 v115, v86
	ds_read_b128 v[86:89], v213 offset:480
	ds_read_b128 v[94:97], v219 offset:480
	s_waitcnt lgkmcnt(2)
	v_mfma_f32_32x32x16_bf16 v[98:113], v[90:93], v[82:85], v[98:113]
	v_mul_f32_e32 v82, v114, v115
	v_exp_f32_e32 v114, v82
	v_add_u32_e32 v115, s10, v216
	s_waitcnt lgkmcnt(0)
	v_mfma_f32_32x32x16_bf16 v[98:113], v[94:97], v[86:89], v[98:113]
	s_cbranch_scc1 .LBB0_451
	ds_read_b128 v[82:85], v115
	ds_read_b128 v[86:89], v115 offset:16
	ds_read_b128 v[90:93], v115 offset:32
	ds_read_b128 v[94:97], v115 offset:48
	s_waitcnt lgkmcnt(3)
	v_pk_mul_f32 v[84:85], v[114:115], v[84:85] op_sel_hi:[0,1]
	s_waitcnt lgkmcnt(2)
	v_pk_mul_f32 v[88:89], v[114:115], v[88:89] op_sel_hi:[0,1]
	s_waitcnt lgkmcnt(1)
	v_pk_mul_f32 v[92:93], v[114:115], v[92:93] op_sel_hi:[0,1]
	s_waitcnt lgkmcnt(0)
	v_pk_mul_f32 v[96:97], v[114:115], v[96:97] op_sel_hi:[0,1]
	v_pk_mul_f32 v[82:83], v[114:115], v[82:83] op_sel_hi:[0,1]
	v_pk_mul_f32 v[86:87], v[114:115], v[86:87] op_sel_hi:[0,1]
	v_pk_mul_f32 v[90:91], v[114:115], v[90:91] op_sel_hi:[0,1]
	v_pk_mul_f32 v[94:95], v[114:115], v[94:95] op_sel_hi:[0,1]
	v_pk_mul_f32 v[94:95], v[110:111], v[94:95]
	v_pk_mul_f32 v[90:91], v[106:107], v[90:91]
	v_pk_mul_f32 v[86:87], v[102:103], v[86:87]
	v_pk_mul_f32 v[96:97], v[112:113], v[96:97]
	v_pk_mul_f32 v[92:93], v[108:109], v[92:93]
	v_pk_mul_f32 v[88:89], v[104:105], v[88:89]
	v_pk_mul_f32 v[84:85], v[100:101], v[84:85]
	v_pk_mul_f32 v[82:83], v[98:99], v[82:83]
	s_cbranch_execnz .LBB0_446

.LBB0_470:
	s_add_i32 s84, s24, 1
	s_cmp_lt_u32 s84, s46
	s_cselect_b64 s[26:27], -1, 0
	s_cmp_ge_u32 s84, s46
	s_cbranch_scc1 .LBB0_476
	s_cmp_ge_u32 s24, s44
	s_mov_b64 s[34:35], -1
	s_cbranch_scc0 .LBB0_473
	s_add_i32 s4, s81, s24
	s_add_i32 s30, s4, -4
	s_add_i32 s4, s47, s82
	s_lshl_b64 s[10:11], s[4:5], 8
	s_add_u32 s10, s63, s10
	s_mov_b32 s31, s5
	s_addc_u32 s11, s75, s11
	s_lshl_b64 s[30:31], s[30:31], 14
	s_add_u32 s30, s78, s30
	s_addc_u32 s31, s79, s31
	s_mov_b64 s[34:35], 0

.LBB0_480:
	s_bitcmp1_b32 s24, 0
	s_cselect_b32 s4, 0x8800, 0
	s_add_i32 s4, s4, 0
	v_add3_u32 v21, s4, v162, v175
	ds_read_b128 v[22:25], v21
	ds_read_b128 v[26:29], v21 offset:32
	v_mul_u32_u24_e32 v18, s30, v183
	v_lshlrev_b32_e32 v18, 1, v18
	v_mov_b32_e32 v173, v19
	s_waitcnt lgkmcnt(1)
	v_mfma_f32_32x32x16_bf16 v[98:113], v[22:25], v[138:141], 0
	s_cmp_gt_u32 s24, s44
	s_waitcnt lgkmcnt(0)
	v_mfma_f32_32x32x16_bf16 v[98:113], v[26:29], v[114:117], v[98:113]
	ds_read_b128 v[22:25], v21 offset:64
	ds_read_b128 v[26:29], v21 offset:96
	s_waitcnt lgkmcnt(1)
	v_mfma_f32_32x32x16_bf16 v[98:113], v[22:25], v[118:121], v[98:113]
	s_waitcnt lgkmcnt(0)
	v_mfma_f32_32x32x16_bf16 v[98:113], v[26:29], v[122:125], v[98:113]
	ds_read_b128 v[22:25], v21 offset:128
	ds_read_b128 v[26:29], v21 offset:160
	s_waitcnt lgkmcnt(1)
	v_mfma_f32_32x32x16_bf16 v[98:113], v[22:25], v[126:129], v[98:113]
	s_waitcnt lgkmcnt(0)
	v_mfma_f32_32x32x16_bf16 v[98:113], v[26:29], v[130:133], v[98:113]
	ds_read_b128 v[22:25], v21 offset:192
	ds_read_b128 v[26:29], v21 offset:224
	s_waitcnt lgkmcnt(1)
	v_mfma_f32_32x32x16_bf16 v[98:113], v[22:25], v[134:137], v[98:113]
	s_waitcnt lgkmcnt(0)
	v_mfma_f32_32x32x16_bf16 v[98:113], v[26:29], v[142:145], v[98:113]
	ds_read_b128 v[22:25], v21 offset:8704
	ds_read_b128 v[26:29], v21 offset:8736
	s_waitcnt lgkmcnt(1)
	v_mfma_f32_32x32x16_bf16 v[82:97], v[22:25], v[138:141], 0
	s_waitcnt lgkmcnt(0)
	v_mfma_f32_32x32x16_bf16 v[82:97], v[26:29], v[114:117], v[82:97]
	ds_read_b128 v[22:25], v21 offset:8768
	ds_read_b128 v[26:29], v21 offset:8800
	s_waitcnt lgkmcnt(1)
	v_mfma_f32_32x32x16_bf16 v[82:97], v[22:25], v[118:121], v[82:97]
	s_waitcnt lgkmcnt(0)
	v_mfma_f32_32x32x16_bf16 v[82:97], v[26:29], v[122:125], v[82:97]
	ds_read_b128 v[22:25], v21 offset:8832
	ds_read_b128 v[26:29], v21 offset:8864
	s_waitcnt lgkmcnt(1)
	v_mfma_f32_32x32x16_bf16 v[82:97], v[22:25], v[126:129], v[82:97]
	ds_read_b128 v[22:25], v21 offset:8896
	s_waitcnt lgkmcnt(1)
	v_mfma_f32_32x32x16_bf16 v[82:97], v[26:29], v[130:133], v[82:97]
	v_lshl_add_u64 v[26:27], s[10:11], 0, v[18:19]
	v_lshl_add_u64 v[30:31], v[26:27], 0, v[172:173]
	ds_read_b128 v[26:29], v21 offset:8928
	global_load_dword v252, v[30:31], off
	s_waitcnt lgkmcnt(1)
	v_mfma_f32_32x32x16_bf16 v[82:97], v[22:25], v[134:137], v[82:97]
	s_waitcnt lgkmcnt(0)
	v_mfma_f32_32x32x16_bf16 v[82:97], v[26:29], v[142:145], v[82:97]
	s_cbranch_scc1 .LBB0_482
	v_add_u32_e32 v18, s47, v186
	v_add_co_u32_e32 v22, vcc, 0xfffffeff, v18
	v_add_u32_e32 v22, 0xffffff00, v18
	s_nop 0
	v_cndmask_b32_e32 v98, v98, v187, vcc
	v_cmp_lt_u32_e32 vcc, s83, v22
	v_add_u32_e32 v22, 0xffffff01, v18
	s_nop 0
	v_cndmask_b32_e32 v99, v187, v99, vcc
	v_cmp_lt_u32_e32 vcc, s83, v22
	v_add_u32_e32 v22, 0xffffff02, v18
	s_nop 0
	v_cndmask_b32_e32 v100, v187, v100, vcc
	v_cmp_lt_u32_e32 vcc, s83, v22
	v_add_u32_e32 v22, 0xffffff07, v18
	s_nop 0
	v_cndmask_b32_e32 v101, v187, v101, vcc
	v_cmp_lt_u32_e32 vcc, s83, v22
	v_add_u32_e32 v22, 0xffffff08, v18
	s_nop 0
	v_cndmask_b32_e32 v102, v187, v102, vcc
	v_cmp_lt_u32_e32 vcc, s83, v22
	v_add_u32_e32 v22, 0xffffff09, v18
	s_nop 0
	v_cndmask_b32_e32 v103, v187, v103, vcc
	v_cmp_lt_u32_e32 vcc, s83, v22
	v_add_u32_e32 v22, 0xffffff0a, v18
	s_nop 0
	v_cndmask_b32_e32 v104, v187, v104, vcc
	v_cmp_lt_u32_e32 vcc, s83, v22
	v_add_u32_e32 v22, 0xffffff0f, v18
	s_nop 0
	v_cndmask_b32_e32 v105, v187, v105, vcc
	v_cmp_lt_u32_e32 vcc, s83, v22
	v_add_u32_e32 v22, 0xffffff10, v18
	s_nop 0
	v_cndmask_b32_e32 v106, v187, v106, vcc
	v_cmp_lt_u32_e32 vcc, s83, v22
	v_add_u32_e32 v22, 0xffffff11, v18
	s_nop 0
	v_cndmask_b32_e32 v107, v187, v107, vcc
	v_cmp_lt_u32_e32 vcc, s83, v22
	v_add_u32_e32 v22, 0xffffff12, v18
	s_nop 0
	v_cndmask_b32_e32 v108, v187, v108, vcc
	v_cmp_lt_u32_e32 vcc, s83, v22
	v_add_u32_e32 v22, 0xffffff17, v18
	s_nop 0
	v_cndmask_b32_e32 v109, v187, v109, vcc
	v_cmp_lt_u32_e32 vcc, s83, v22
	v_add_u32_e32 v22, 0xffffff18, v18
	s_nop 0
	v_cndmask_b32_e32 v110, v187, v110, vcc
	v_cmp_lt_u32_e32 vcc, s83, v22
	v_add_u32_e32 v22, 0xffffff19, v18
	s_nop 0
	v_cndmask_b32_e32 v111, v187, v111, vcc
	v_cmp_lt_u32_e32 vcc, s83, v22
	v_add_u32_e32 v22, 0xffffff1a, v18
	s_nop 0
	v_cndmask_b32_e32 v112, v187, v112, vcc
	v_cmp_lt_u32_e32 vcc, s83, v22
	v_add_u32_e32 v22, 0xffffff1f, v18
	s_nop 0
	v_cndmask_b32_e32 v113, v187, v113, vcc
	v_cmp_lt_u32_e32 vcc, s83, v22
	v_add_u32_e32 v22, 0xffffff20, v18
	s_nop 0
	v_cndmask_b32_e32 v82, v187, v82, vcc
	v_cmp_lt_u32_e32 vcc, s83, v22
	v_add_u32_e32 v22, 0xffffff21, v18
	s_nop 0
	v_cndmask_b32_e32 v83, v187, v83, vcc
	v_cmp_lt_u32_e32 vcc, s83, v22
	v_add_u32_e32 v22, 0xffffff22, v18
	s_nop 0
	v_cndmask_b32_e32 v84, v187, v84, vcc
	v_cmp_lt_u32_e32 vcc, s83, v22
	v_add_u32_e32 v22, 0xffffff27, v18
	s_nop 0
	v_cndmask_b32_e32 v85, v187, v85, vcc
	v_cmp_lt_u32_e32 vcc, s83, v22
	v_add_u32_e32 v22, 0xffffff28, v18
	s_nop 0
	v_cndmask_b32_e32 v86, v187, v86, vcc
	v_cmp_lt_u32_e32 vcc, s83, v22
	v_add_u32_e32 v22, 0xffffff29, v18
	s_nop 0
	v_cndmask_b32_e32 v87, v187, v87, vcc
	v_cmp_lt_u32_e32 vcc, s83, v22
	v_add_u32_e32 v22, 0xffffff2a, v18
	s_nop 0
	v_cndmask_b32_e32 v88, v187, v88, vcc
	v_cmp_lt_u32_e32 vcc, s83, v22
	v_add_u32_e32 v22, 0xffffff2f, v18
	s_nop 0
	v_cndmask_b32_e32 v89, v187, v89, vcc
	v_cmp_lt_u32_e32 vcc, s83, v22
	v_add_u32_e32 v22, 0xffffff30, v18
	s_nop 0
	v_cndmask_b32_e32 v90, v187, v90, vcc
	v_cmp_lt_u32_e32 vcc, s83, v22
	v_add_u32_e32 v22, 0xffffff31, v18
	s_nop 0
	v_cndmask_b32_e32 v91, v187, v91, vcc
	v_cmp_lt_u32_e32 vcc, s83, v22
	v_add_u32_e32 v22, 0xffffff32, v18
	s_nop 0
	v_cndmask_b32_e32 v92, v187, v92, vcc
	v_cmp_lt_u32_e32 vcc, s83, v22
	v_add_u32_e32 v22, 0xffffff37, v18
	s_nop 0
	v_cndmask_b32_e32 v93, v187, v93, vcc
	v_cmp_lt_u32_e32 vcc, s83, v22
	v_add_u32_e32 v22, 0xffffff38, v18
	s_nop 0
	v_cndmask_b32_e32 v94, v187, v94, vcc
	v_cmp_lt_u32_e32 vcc, s83, v22
	v_add_u32_e32 v22, 0xffffff39, v18
	v_add_u32_e32 v18, 0xffffff3a, v18
	v_cndmask_b32_e32 v95, v187, v95, vcc
	v_cmp_lt_u32_e32 vcc, s83, v22
	s_nop 1
	v_cndmask_b32_e32 v96, v187, v96, vcc
	v_cmp_lt_u32_e32 vcc, s83, v18
	s_nop 1
	v_cndmask_b32_e32 v97, v187, v97, vcc

.LBB0_491:
	s_cmp_lt_u32 s40, 3
	s_cselect_b64 s[38:39], -1, 0
	s_cmp_gt_u32 s40, 2
	s_cbranch_scc1 .LBB0_493
	s_mul_i32 s44, s4, 0x9800
	s_mul_hi_i32 s41, s4, 0x9800
	s_add_u32 s44, s0, s44
	s_addc_u32 s41, s1, s41
	s_add_u32 s44, s44, s25
	s_addc_u32 s41, s41, 0
	s_add_u32 s44, s44, 0x5000
	s_addc_u32 s45, s41, 0
	s_ashr_i32 s46, s4, 6
	s_ashr_i32 s47, s46, 31
	s_lshl_b64 s[46:47], s[46:47], 16
	v_lshl_add_u64 v[66:67], s[44:45], 0, v[168:169]
	v_lshl_add_u64 v[68:69], v[156:157], 0, s[46:47]
	global_load_dwordx4 v[114:117], v[66:67], off
	global_load_dwordx4 v[122:125], v[68:69], off
	v_lshl_add_u64 v[66:67], s[44:45], 0, v[170:171]
	v_add_co_u32_e32 v68, vcc, 0x2000, v68
	s_nop 1
	v_addc_co_u32_e32 v69, vcc, 0, v69, vcc
	global_load_dwordx4 v[126:129], v[66:67], off
	global_load_dwordx4 v[134:137], v[68:69], off
.LBB0_493:
	s_bitcmp1_b32 s40, 0
	s_cselect_b32 s41, 0x8800, 0
	s_add_i32 s41, s41, 0
	v_add3_u32 v183, s41, v162, v175
	ds_read_b128 v[66:69], v183
	ds_read_b128 v[70:73], v183 offset:32
	s_min_i32 s44, s40, 1
	s_lshl_b32 s44, s44, 6
	s_or_b32 s44, s44, s24
	s_waitcnt lgkmcnt(1)
	v_mfma_f32_32x32x16_bf16 v[82:97], v[66:69], v[98:101], 0
	s_mul_hi_i32 s45, s44, 0x9800
	s_mul_i32 s44, s44, 0x9800
	s_add_u32 s44, s0, s44
	s_addc_u32 s45, s1, s45
	s_add_u32 s44, s44, s25
	s_addc_u32 s45, s45, 0
	v_lshl_add_u64 v[176:177], s[44:45], 0, v[148:149]
	s_waitcnt lgkmcnt(0)
	v_mfma_f32_32x32x16_bf16 v[82:97], v[70:73], v[102:105], v[82:97]
	ds_read_b128 v[66:69], v183 offset:64
	ds_read_b128 v[70:73], v183 offset:96
	v_mov_b32_e32 v173, v149
	v_lshl_add_u64 v[176:177], v[176:177], 0, v[172:173]
	v_add_co_u32_e32 v176, vcc, s35, v176
	s_nop 1
	v_addc_co_u32_e32 v177, vcc, 0, v177, vcc
	s_waitcnt lgkmcnt(1)
	v_mfma_f32_32x32x16_bf16 v[82:97], v[66:69], v[106:109], v[82:97]
	s_waitcnt lgkmcnt(0)
	v_mfma_f32_32x32x16_bf16 v[82:97], v[70:73], v[110:113], v[82:97]
	ds_read_b128 v[66:69], v183 offset:128
	ds_read_b128 v[70:73], v183 offset:160
	s_waitcnt lgkmcnt(1)
	v_mfma_f32_32x32x16_bf16 v[82:97], v[66:69], v[118:121], v[82:97]
	s_waitcnt lgkmcnt(0)
	v_mfma_f32_32x32x16_bf16 v[82:97], v[70:73], v[130:133], v[82:97]
	ds_read_b128 v[66:69], v183 offset:192
	ds_read_b128 v[70:73], v183 offset:224
	s_waitcnt lgkmcnt(1)
	v_mfma_f32_32x32x16_bf16 v[82:97], v[66:69], v[138:141], v[82:97]
	ds_read_b128 v[66:69], v183 offset:8704
	ds_read_b128 v[184:187], v183 offset:8736
	global_load_dword v252, v[176:177], off
	ds_read_b128 v[188:191], v183 offset:8800
	s_waitcnt lgkmcnt(3)
	v_mfma_f32_32x32x16_bf16 v[82:97], v[70:73], v[142:145], v[82:97]
	s_waitcnt lgkmcnt(2)
	v_mfma_f32_32x32x16_bf16 v[66:81], v[66:69], v[98:101], 0
	s_nop 9
	v_max_f32_e32 v173, v83, v83
	v_max_f32_e32 v176, v82, v82
	v_max_f32_e32 v173, v176, v173
	v_max3_f32 v173, v173, v84, v85
	v_max3_f32 v173, v173, v86, v87
	v_max3_f32 v173, v173, v88, v89
	v_max3_f32 v173, v173, v90, v91
	s_waitcnt lgkmcnt(1)
	v_mfma_f32_32x32x16_bf16 v[66:81], v[184:187], v[102:105], v[66:81]
	ds_read_b128 v[184:187], v183 offset:8768
	v_max3_f32 v173, v173, v92, v93
	v_max3_f32 v173, v173, v94, v95
	v_max3_f32 v173, v173, v96, v97
	s_waitcnt lgkmcnt(0)
	v_mfma_f32_32x32x16_bf16 v[66:81], v[184:187], v[106:109], v[66:81]
	ds_read_b128 v[184:187], v183 offset:8832
	v_mfma_f32_32x32x16_bf16 v[66:81], v[188:191], v[110:113], v[66:81]
	ds_read_b128 v[188:191], v183 offset:8864
	s_waitcnt lgkmcnt(1)
	v_mfma_f32_32x32x16_bf16 v[66:81], v[184:187], v[118:121], v[66:81]
	s_waitcnt lgkmcnt(0)
	v_mfma_f32_32x32x16_bf16 v[66:81], v[188:191], v[130:133], v[66:81]
	ds_read_b128 v[184:187], v183 offset:8896
	ds_read_b128 v[188:191], v183 offset:8928
	s_waitcnt lgkmcnt(1)
	v_mfma_f32_32x32x16_bf16 v[66:81], v[184:187], v[138:141], v[66:81]
	s_waitcnt lgkmcnt(0)
	v_mfma_f32_32x32x16_bf16 v[66:81], v[188:191], v[142:145], v[66:81]
	s_nop 11
	v_max3_f32 v173, v173, v66, v67
	v_max3_f32 v173, v173, v68, v69
	v_max3_f32 v173, v173, v70, v71
	v_max3_f32 v173, v173, v72, v73
	v_max3_f32 v173, v173, v74, v75
	v_max3_f32 v173, v173, v76, v77
	v_max3_f32 v173, v173, v78, v79
	v_max3_f32 v173, v173, v80, v81
	v_mov_b32_e32 v176, v173
	s_nop 1
	v_permlane32_swap_b32_e32 v173, v176
	v_max3_f32 v173, v158, v173, v176
	v_cmp_gt_f32_e32 vcc, v173, v158
	v_sub_f32_e32 v158, v158, v173
	v_exp_f32_e32 v158, v158
	s_cmp_eq_u64 vcc, 0
	s_cselect_b64 s[46:47], -1, 0
	s_and_b64 vcc, exec, s[46:47]
	s_cbranch_vccnz .LBB0_495
	v_pk_mul_f32 v[64:65], v[64:65], v[158:159] op_sel_hi:[1,0]
	v_pk_mul_f32 v[62:63], v[62:63], v[158:159] op_sel_hi:[1,0]
	v_pk_mul_f32 v[60:61], v[60:61], v[158:159] op_sel_hi:[1,0]
	v_pk_mul_f32 v[58:59], v[58:59], v[158:159] op_sel_hi:[1,0]
	v_pk_mul_f32 v[56:57], v[56:57], v[158:159] op_sel_hi:[1,0]
	v_pk_mul_f32 v[54:55], v[54:55], v[158:159] op_sel_hi:[1,0]
	v_pk_mul_f32 v[52:53], v[52:53], v[158:159] op_sel_hi:[1,0]
	v_pk_mul_f32 v[50:51], v[50:51], v[158:159] op_sel_hi:[1,0]
	v_pk_mul_f32 v[48:49], v[48:49], v[158:159] op_sel_hi:[1,0]
	v_pk_mul_f32 v[46:47], v[46:47], v[158:159] op_sel_hi:[1,0]
	v_pk_mul_f32 v[44:45], v[44:45], v[158:159] op_sel_hi:[1,0]
	v_pk_mul_f32 v[42:43], v[42:43], v[158:159] op_sel_hi:[1,0]
	v_pk_mul_f32 v[40:41], v[40:41], v[158:159] op_sel_hi:[1,0]
	v_pk_mul_f32 v[38:39], v[38:39], v[158:159] op_sel_hi:[1,0]
	v_pk_mul_f32 v[36:37], v[36:37], v[158:159] op_sel_hi:[1,0]
	v_pk_mul_f32 v[34:35], v[34:35], v[158:159] op_sel_hi:[1,0]
	v_pk_mul_f32 v[32:33], v[32:33], v[158:159] op_sel_hi:[1,0]
	v_pk_mul_f32 v[30:31], v[30:31], v[158:159] op_sel_hi:[1,0]
	v_pk_mul_f32 v[28:29], v[28:29], v[158:159] op_sel_hi:[1,0]
	v_pk_mul_f32 v[26:27], v[26:27], v[158:159] op_sel_hi:[1,0]
	v_pk_mul_f32 v[24:25], v[24:25], v[158:159] op_sel_hi:[1,0]
	v_pk_mul_f32 v[22:23], v[22:23], v[158:159] op_sel_hi:[1,0]
	v_pk_mul_f32 v[20:21], v[20:21], v[158:159] op_sel_hi:[1,0]
	v_pk_mul_f32 v[18:19], v[18:19], v[158:159] op_sel_hi:[1,0]
	v_pk_mul_f32 v[16:17], v[16:17], v[158:159] op_sel_hi:[1,0]
	v_pk_mul_f32 v[14:15], v[14:15], v[158:159] op_sel_hi:[1,0]
	v_pk_mul_f32 v[12:13], v[12:13], v[158:159] op_sel_hi:[1,0]
	v_pk_mul_f32 v[10:11], v[10:11], v[158:159] op_sel_hi:[1,0]
	v_pk_mul_f32 v[8:9], v[8:9], v[158:159] op_sel_hi:[1,0]
	v_pk_mul_f32 v[6:7], v[6:7], v[158:159] op_sel_hi:[1,0]
	v_pk_mul_f32 v[4:5], v[4:5], v[158:159] op_sel_hi:[1,0]
	v_pk_mul_f32 v[2:3], v[2:3], v[158:159] op_sel_hi:[1,0]
